# attention: next unit's addresses, Q fragments and first three K/V tiles requested before the current unit's output is written
# baseline (speedup 1.0000x reference)
.Lat2_noprio:
	v_and_b32_e32 v228, 31, v246
	v_lshrrev_b32_e32 v229, 5, v246
	v_lshlrev_b32_e32 v200, 10, v246
	s_lshl_b32 s4, s27, 4
	v_add_u32_e32 v200, s4, v200
	v_lshrrev_b32_e32 v230, 2, v246
	s_and_b32 s4, s27, 3
	s_lshl_b32 s4, s4, 4
	v_add_u32_e32 v230, s4, v230
	v_lshlrev_b32_e32 v230, 10, v230
	v_and_b32_e32 v231, 3, v246
	v_lshlrev_b32_e32 v231, 4, v231
	s_lshr_b32 s4, s27, 2
	s_lshl_b32 s4, s4, 6
	v_add3_u32 v201, v230, v231, s4
	v_add_u32_e32 v202, 0x80, v201
	s_lshl_b32 s4, s27, 5
	v_add_u32_e32 v230, s4, v228
	v_lshlrev_b32_e32 v225, 10, v230
	v_lshl_add_u32 v225, v229, 4, v225
	v_lshlrev_b32_e32 v231, 2, v229
	v_sub_u32_e32 v218, v230, v231
	v_lshlrev_b32_e32 v203, 10, v229
	v_lshl_add_u32 v203, v228, 4, v203
	v_bfe_u32 v230, v246, 4, 1
	v_lshlrev_b32_e32 v230, 5, v230
	v_and_b32_e32 v231, 3, v246
	v_lshl_add_u32 v230, v231, 3, v230
	v_bfe_u32 v231, v246, 2, 2
	v_lshl_add_u32 v231, v229, 2, v231
	v_lshl_add_u32 v230, v231, 6, v230
	v_add_u32_e32 v204, 0x8000, v230
	s_lshl_b32 s4, s27, 8
	s_add_i32 s4, s4, 0x18000
	v_lshl_add_u32 v220, v228, 2, s4
	v_lshl_add_u32 v221, v229, 4, s4
	s_lshl_b32 s4, s27, 11
	s_add_i32 s4, s4, 0x18800
	v_lshlrev_b32_e32 v230, 8, v229
	v_lshl_add_u32 v230, v228, 1, v230
	v_add_u32_e32 v222, s4, v230
	v_lshrrev_b32_e32 v230, 2, v246
	v_and_b32_e32 v231, 3, v246
	v_lshlrev_b32_e32 v223, 6, v230
	v_lshl_add_u32 v223, v231, 4, v223
	v_add_u32_e32 v223, s4, v223
	s_lshl_b32 s4, s27, 5
	v_add_u32_e32 v230, s4, v230
	v_lshlrev_b32_e32 v224, 11, v230
	v_lshl_add_u32 v224, v231, 4, v224
	v_mov_b32_e32 v219, 0xff800000
	s_mov_b32 s26, 0
	s_and_b32 s4, s38, 3
	s_lshl_b32 s4, s4, 1
	s_lshr_b32 s5, s26, 1
	s_add_i32 s4, s4, s5
	s_sub_i32 s5, 15, s4
	s_bitcmp1_b32 s26, 0
	s_cselect_b32 s4, s4, s5
	s_lshl_b32 s39, s4, 2
	s_add_i32 s39, s39, 4
	s_sub_i32 s18, s39, 4
	s_lshr_b32 s5, s38, 5
	s_lshl_b32 s5, s5, 12
	s_lshl_b32 s6, s4, 8
	s_add_i32 s6, s6, s5
	s_bfe_u32 s7, s38, 0x30002
	s_lshl_b32 s14, s6, 10
	s_lshl_b32 s15, s7, 7
	s_add_i32 s14, s14, s15
	s_add_u32 s72, s54, s14
	s_addc_u32 s73, s55, 0
	s_lshl_b32 s14, s5, 10
	s_add_i32 s15, s14, s15
	s_add_i32 s15, s15, 0x2000000
	s_add_u32 s74, s54, s15
	s_addc_u32 s75, s55, 0
	s_lshr_b32 s15, s7, 1
	s_lshl_b32 s15, s15, 8
	s_add_i32 s14, s14, s15
	s_add_u32 s76, s64, s14
	s_addc_u32 s77, s65, 0
	s_lshl_b32 s14, s6, 11
	s_lshl_b32 s15, s7, 8
	s_add_i32 s14, s14, s15
	s_add_u32 s78, s50, s14
	s_addc_u32 s79, s51, 0
	global_load_dwordx4 v[148:151], v225, s[72:73] offset:0
	global_load_dwordx4 v[152:155], v225, s[72:73] offset:32
	global_load_dwordx4 v[156:159], v225, s[72:73] offset:64
	global_load_dwordx4 v[160:163], v225, s[72:73] offset:96
	s_mov_b64 s[80:81], s[74:75]
	s_mov_b64 s[82:83], s[76:77]
	s_mov_b32 s59, 0
	s_mov_b32 s60, 0x2000
	s_mov_b32 s61, 0x4000
	s_mov_b32 s25, 0x6000
	s_add_i32 s4, s59, s16
	s_mov_b32 m0, s4
	s_lshl_b32 s5, s59, 1
	global_load_lds_dwordx4 v200, s[80:81]
	s_add_i32 s5, s5, s16
	s_add_i32 s5, s5, 0x8000
	s_mov_b32 m0, s5
	s_add_i32 s5, s5, 0x2000
	global_load_lds_dwordx4 v201, s[82:83]
	s_mov_b32 m0, s5
	s_nop 0
	global_load_lds_dwordx4 v202, s[82:83]
	s_add_u32 s80, s80, 0x10000
	s_addc_u32 s81, s81, 0
	s_add_u32 s82, s82, 0x10000
	s_addc_u32 s83, s83, 0
	s_add_i32 s4, s60, s16
	s_mov_b32 m0, s4
	s_lshl_b32 s5, s60, 1
	global_load_lds_dwordx4 v200, s[80:81]
	s_add_i32 s5, s5, s16
	s_add_i32 s5, s5, 0x8000
	s_mov_b32 m0, s5
	s_add_i32 s5, s5, 0x2000
	global_load_lds_dwordx4 v201, s[82:83]
	s_mov_b32 m0, s5
	s_nop 0
	global_load_lds_dwordx4 v202, s[82:83]
	s_add_u32 s80, s80, 0x10000
	s_addc_u32 s81, s81, 0
	s_add_u32 s82, s82, 0x10000
	s_addc_u32 s83, s83, 0
	s_add_i32 s4, s61, s16
	s_mov_b32 m0, s4
	s_lshl_b32 s5, s61, 1
	global_load_lds_dwordx4 v200, s[80:81]
	s_add_i32 s5, s5, s16
	s_add_i32 s5, s5, 0x8000
	s_mov_b32 m0, s5
	s_add_i32 s5, s5, 0x2000
	global_load_lds_dwordx4 v201, s[82:83]
	s_mov_b32 m0, s5
	s_nop 0
	global_load_lds_dwordx4 v202, s[82:83]
	s_add_u32 s80, s80, 0x10000
	s_addc_u32 s81, s81, 0
	s_add_u32 s82, s82, 0x10000
	s_addc_u32 s83, s83, 0
.Lat2_unit_1:
	v_mov_b32_e32 v0, 0
	v_mov_b32_e32 v1, 0
	v_mov_b32_e32 v2, 0
	v_mov_b32_e32 v3, 0
	v_mov_b32_e32 v4, 0
	v_mov_b32_e32 v5, 0
	v_mov_b32_e32 v6, 0
	v_mov_b32_e32 v7, 0
	v_mov_b32_e32 v8, 0
	v_mov_b32_e32 v9, 0
	v_mov_b32_e32 v10, 0
	v_mov_b32_e32 v11, 0
	v_mov_b32_e32 v12, 0
	v_mov_b32_e32 v13, 0
	v_mov_b32_e32 v14, 0
	v_mov_b32_e32 v15, 0
	v_mov_b32_e32 v16, 0
	v_mov_b32_e32 v17, 0
	v_mov_b32_e32 v18, 0
	v_mov_b32_e32 v19, 0
	v_mov_b32_e32 v20, 0
	v_mov_b32_e32 v21, 0
	v_mov_b32_e32 v22, 0
	v_mov_b32_e32 v23, 0
	v_mov_b32_e32 v24, 0
	v_mov_b32_e32 v25, 0
	v_mov_b32_e32 v26, 0
	v_mov_b32_e32 v27, 0
	v_mov_b32_e32 v28, 0
	v_mov_b32_e32 v29, 0
	v_mov_b32_e32 v30, 0
	v_mov_b32_e32 v31, 0
	v_mov_b32_e32 v32, 0
	v_mov_b32_e32 v33, 0
	v_mov_b32_e32 v34, 0
	v_mov_b32_e32 v35, 0
	v_mov_b32_e32 v36, 0
	v_mov_b32_e32 v37, 0
	v_mov_b32_e32 v38, 0
	v_mov_b32_e32 v39, 0
	v_mov_b32_e32 v40, 0
	v_mov_b32_e32 v41, 0
	v_mov_b32_e32 v42, 0
	v_mov_b32_e32 v43, 0
	v_mov_b32_e32 v44, 0
	v_mov_b32_e32 v45, 0
	v_mov_b32_e32 v46, 0
	v_mov_b32_e32 v47, 0
	v_mov_b32_e32 v48, 0
	v_mov_b32_e32 v49, 0
	v_mov_b32_e32 v50, 0
	v_mov_b32_e32 v51, 0
	v_mov_b32_e32 v52, 0
	v_mov_b32_e32 v53, 0
	v_mov_b32_e32 v54, 0
	v_mov_b32_e32 v55, 0
	v_mov_b32_e32 v56, 0
	v_mov_b32_e32 v57, 0
	v_mov_b32_e32 v58, 0
	v_mov_b32_e32 v59, 0
	v_mov_b32_e32 v60, 0
	v_mov_b32_e32 v61, 0
	v_mov_b32_e32 v62, 0
	v_mov_b32_e32 v63, 0
	v_mov_b32_e32 v100, 0
	v_mov_b32_e32 v101, 0
	v_mov_b32_e32 v102, 0
	v_mov_b32_e32 v103, 0
	v_mov_b32_e32 v104, 0
	v_mov_b32_e32 v105, 0
	v_mov_b32_e32 v106, 0
	v_mov_b32_e32 v107, 0
	v_mov_b32_e32 v108, 0
	v_mov_b32_e32 v109, 0
	v_mov_b32_e32 v110, 0
	v_mov_b32_e32 v111, 0
	v_mov_b32_e32 v112, 0
	v_mov_b32_e32 v113, 0
	v_mov_b32_e32 v114, 0
	v_mov_b32_e32 v115, 0
	v_mov_b32_e32 v210, 0
	v_mov_b32_e32 v232, 0
	v_mov_b32_e32 v233, 0
	v_mov_b32_e32 v234, 0
	v_mov_b32_e32 v235, 0
	s_mov_b32 s62, 0xf149f2ca
	s_mov_b32 s47, 0xf149f2ca
	s_mov_b32 s45, 0
	s_cmp_eq_u32 s26, 0
	s_cbranch_scc1 .Lat2_first_2
	s_waitcnt vmcnt(14)
	s_branch .Lat2_go_3

.Lat2_go_3:
	s_barrier
	s_cmp_lt_u32 s45, s18
	s_cbranch_scc0 .Lat2_band_5

.Lat2_skip_26:
	s_mov_b64 s[0:1], s[78:79]
	s_add_i32 s26, s26, 1
	s_cmp_lt_u32 s26, 4
	s_cbranch_scc0 .Lat2_nopf_30
	s_and_b32 s4, s38, 3
	s_lshl_b32 s4, s4, 1
	s_lshr_b32 s5, s26, 1
	s_add_i32 s4, s4, s5
	s_sub_i32 s5, 15, s4
	s_bitcmp1_b32 s26, 0
	s_cselect_b32 s4, s4, s5
	s_lshl_b32 s39, s4, 2
	s_add_i32 s39, s39, 4
	s_sub_i32 s18, s39, 4
	s_lshr_b32 s5, s38, 5
	s_lshl_b32 s5, s5, 12
	s_lshl_b32 s6, s4, 8
	s_add_i32 s6, s6, s5
	s_bfe_u32 s7, s38, 0x30002
	s_lshl_b32 s14, s6, 10
	s_lshl_b32 s15, s7, 7
	s_add_i32 s14, s14, s15
	s_add_u32 s72, s54, s14
	s_addc_u32 s73, s55, 0
	s_lshl_b32 s14, s5, 10
	s_add_i32 s15, s14, s15
	s_add_i32 s15, s15, 0x2000000
	s_add_u32 s74, s54, s15
	s_addc_u32 s75, s55, 0
	s_lshr_b32 s15, s7, 1
	s_lshl_b32 s15, s15, 8
	s_add_i32 s14, s14, s15
	s_add_u32 s76, s64, s14
	s_addc_u32 s77, s65, 0
	s_lshl_b32 s14, s6, 11
	s_lshl_b32 s15, s7, 8
	s_add_i32 s14, s14, s15
	s_add_u32 s78, s50, s14
	s_addc_u32 s79, s51, 0
	global_load_dwordx4 v[148:151], v225, s[72:73] offset:0
	global_load_dwordx4 v[152:155], v225, s[72:73] offset:32
	global_load_dwordx4 v[156:159], v225, s[72:73] offset:64
	global_load_dwordx4 v[160:163], v225, s[72:73] offset:96
	s_mov_b64 s[80:81], s[74:75]
	s_mov_b64 s[82:83], s[76:77]
	s_mov_b32 s59, 0
	s_mov_b32 s60, 0x2000
	s_mov_b32 s61, 0x4000
	s_mov_b32 s25, 0x6000
	s_add_i32 s4, s59, s16
	s_mov_b32 m0, s4
	s_lshl_b32 s5, s59, 1
	global_load_lds_dwordx4 v200, s[80:81]
	s_add_i32 s5, s5, s16
	s_add_i32 s5, s5, 0x8000
	s_mov_b32 m0, s5
	s_add_i32 s5, s5, 0x2000
	global_load_lds_dwordx4 v201, s[82:83]
	s_mov_b32 m0, s5
	s_nop 0
	global_load_lds_dwordx4 v202, s[82:83]
	s_add_u32 s80, s80, 0x10000
	s_addc_u32 s81, s81, 0
	s_add_u32 s82, s82, 0x10000
	s_addc_u32 s83, s83, 0
	s_add_i32 s4, s60, s16
	s_mov_b32 m0, s4
	s_lshl_b32 s5, s60, 1
	global_load_lds_dwordx4 v200, s[80:81]
	s_add_i32 s5, s5, s16
	s_add_i32 s5, s5, 0x8000
	s_mov_b32 m0, s5
	s_add_i32 s5, s5, 0x2000
	global_load_lds_dwordx4 v201, s[82:83]
	s_mov_b32 m0, s5
	s_nop 0
	global_load_lds_dwordx4 v202, s[82:83]
	s_add_u32 s80, s80, 0x10000
	s_addc_u32 s81, s81, 0
	s_add_u32 s82, s82, 0x10000
	s_addc_u32 s83, s83, 0
	s_add_i32 s4, s61, s16
	s_mov_b32 m0, s4
	s_lshl_b32 s5, s61, 1
	global_load_lds_dwordx4 v200, s[80:81]
	s_add_i32 s5, s5, s16
	s_add_i32 s5, s5, 0x8000
	s_mov_b32 m0, s5
	s_add_i32 s5, s5, 0x2000
	global_load_lds_dwordx4 v201, s[82:83]
	s_mov_b32 m0, s5
	s_nop 0
	global_load_lds_dwordx4 v202, s[82:83]
	s_add_u32 s80, s80, 0x10000
	s_addc_u32 s81, s81, 0
	s_add_u32 s82, s82, 0x10000
	s_addc_u32 s83, s83, 0
.Lat2_nopf_30:
	v_add_f32_e32 v232, v232, v233
	v_add_f32_e32 v234, v234, v235
	v_add_f32_e32 v216, v232, v234
	v_mov_b32_e32 v215, v216
	s_nop 1
	v_permlane32_swap_b32_e32 v216, v215
	s_nop 0
	v_add_f32_e32 v216, v216, v215
	v_rcp_f32_e32 v217, v216
	s_nop 0
	ds_write_b32 v220, v217
	s_waitcnt lgkmcnt(0)
	ds_read_b128 v[116:119], v221 offset:0
	ds_read_b128 v[120:123], v221 offset:32
	ds_read_b128 v[124:127], v221 offset:64
	ds_read_b128 v[128:131], v221 offset:96
	v_add_u32_e32 v229, 0x8000, v224
	s_waitcnt lgkmcnt(0)
	v_mul_f32_e32 v0, v0, v116
	v_mul_f32_e32 v1, v1, v117
	v_cvt_pk_bf16_f32 v0, v0, v1
	ds_write_b16 v222, v0 offset:0
	ds_write_b16_d16_hi v222, v0 offset:64
	v_mul_f32_e32 v2, v2, v118
	v_mul_f32_e32 v3, v3, v119
	v_cvt_pk_bf16_f32 v2, v2, v3
	ds_write_b16 v222, v2 offset:128
	ds_write_b16_d16_hi v222, v2 offset:192
	v_mul_f32_e32 v4, v4, v120
	v_mul_f32_e32 v5, v5, v121
	v_cvt_pk_bf16_f32 v4, v4, v5
	ds_write_b16 v222, v4 offset:512
	ds_write_b16_d16_hi v222, v4 offset:576
	v_mul_f32_e32 v6, v6, v122
	v_mul_f32_e32 v7, v7, v123
	v_cvt_pk_bf16_f32 v6, v6, v7
	ds_write_b16 v222, v6 offset:640
	ds_write_b16_d16_hi v222, v6 offset:704
	v_mul_f32_e32 v8, v8, v124
	v_mul_f32_e32 v9, v9, v125
	v_cvt_pk_bf16_f32 v8, v8, v9
	ds_write_b16 v222, v8 offset:1024
	ds_write_b16_d16_hi v222, v8 offset:1088
	v_mul_f32_e32 v10, v10, v126
	v_mul_f32_e32 v11, v11, v127
	v_cvt_pk_bf16_f32 v10, v10, v11
	ds_write_b16 v222, v10 offset:1152
	ds_write_b16_d16_hi v222, v10 offset:1216
	v_mul_f32_e32 v12, v12, v128
	v_mul_f32_e32 v13, v13, v129
	v_cvt_pk_bf16_f32 v12, v12, v13
	ds_write_b16 v222, v12 offset:1536
	ds_write_b16_d16_hi v222, v12 offset:1600
	v_mul_f32_e32 v14, v14, v130
	v_mul_f32_e32 v15, v15, v131
	v_cvt_pk_bf16_f32 v14, v14, v15
	ds_write_b16 v222, v14 offset:1664
	ds_write_b16_d16_hi v222, v14 offset:1728
	s_waitcnt lgkmcnt(0)
	ds_read_b128 v[132:135], v223
	ds_read_b128 v[136:139], v223 offset:1024
	s_waitcnt lgkmcnt(1)
	global_store_dwordx4 v224, v[132:135], s[0:1] offset:0
	s_waitcnt lgkmcnt(0)
	global_store_dwordx4 v229, v[136:139], s[0:1] offset:0
	v_mul_f32_e32 v16, v16, v116
	v_mul_f32_e32 v17, v17, v117
	v_cvt_pk_bf16_f32 v16, v16, v17
	ds_write_b16 v222, v16 offset:0
	ds_write_b16_d16_hi v222, v16 offset:64
	v_mul_f32_e32 v18, v18, v118
	v_mul_f32_e32 v19, v19, v119
	v_cvt_pk_bf16_f32 v18, v18, v19
	ds_write_b16 v222, v18 offset:128
	ds_write_b16_d16_hi v222, v18 offset:192
	v_mul_f32_e32 v20, v20, v120
	v_mul_f32_e32 v21, v21, v121
	v_cvt_pk_bf16_f32 v20, v20, v21
	ds_write_b16 v222, v20 offset:512
	ds_write_b16_d16_hi v222, v20 offset:576
	v_mul_f32_e32 v22, v22, v122
	v_mul_f32_e32 v23, v23, v123
	v_cvt_pk_bf16_f32 v22, v22, v23
	ds_write_b16 v222, v22 offset:640
	ds_write_b16_d16_hi v222, v22 offset:704
	v_mul_f32_e32 v24, v24, v124
	v_mul_f32_e32 v25, v25, v125
	v_cvt_pk_bf16_f32 v24, v24, v25
	ds_write_b16 v222, v24 offset:1024
	ds_write_b16_d16_hi v222, v24 offset:1088
	v_mul_f32_e32 v26, v26, v126
	v_mul_f32_e32 v27, v27, v127
	v_cvt_pk_bf16_f32 v26, v26, v27
	ds_write_b16 v222, v26 offset:1152
	ds_write_b16_d16_hi v222, v26 offset:1216
	v_mul_f32_e32 v28, v28, v128
	v_mul_f32_e32 v29, v29, v129
	v_cvt_pk_bf16_f32 v28, v28, v29
	ds_write_b16 v222, v28 offset:1536
	ds_write_b16_d16_hi v222, v28 offset:1600
	v_mul_f32_e32 v30, v30, v130
	v_mul_f32_e32 v31, v31, v131
	v_cvt_pk_bf16_f32 v30, v30, v31
	ds_write_b16 v222, v30 offset:1664
	ds_write_b16_d16_hi v222, v30 offset:1728
	s_waitcnt lgkmcnt(0)
	ds_read_b128 v[132:135], v223
	ds_read_b128 v[136:139], v223 offset:1024
	s_waitcnt lgkmcnt(1)
	global_store_dwordx4 v224, v[132:135], s[0:1] offset:64
	s_waitcnt lgkmcnt(0)
	global_store_dwordx4 v229, v[136:139], s[0:1] offset:64
	v_mul_f32_e32 v32, v32, v116
	v_mul_f32_e32 v33, v33, v117
	v_cvt_pk_bf16_f32 v32, v32, v33
	ds_write_b16 v222, v32 offset:0
	ds_write_b16_d16_hi v222, v32 offset:64
	v_mul_f32_e32 v34, v34, v118
	v_mul_f32_e32 v35, v35, v119
	v_cvt_pk_bf16_f32 v34, v34, v35
	ds_write_b16 v222, v34 offset:128
	ds_write_b16_d16_hi v222, v34 offset:192
	v_mul_f32_e32 v36, v36, v120
	v_mul_f32_e32 v37, v37, v121
	v_cvt_pk_bf16_f32 v36, v36, v37
	ds_write_b16 v222, v36 offset:512
	ds_write_b16_d16_hi v222, v36 offset:576
	v_mul_f32_e32 v38, v38, v122
	v_mul_f32_e32 v39, v39, v123
	v_cvt_pk_bf16_f32 v38, v38, v39
	ds_write_b16 v222, v38 offset:640
	ds_write_b16_d16_hi v222, v38 offset:704
	v_mul_f32_e32 v40, v40, v124
	v_mul_f32_e32 v41, v41, v125
	v_cvt_pk_bf16_f32 v40, v40, v41
	ds_write_b16 v222, v40 offset:1024
	ds_write_b16_d16_hi v222, v40 offset:1088
	v_mul_f32_e32 v42, v42, v126
	v_mul_f32_e32 v43, v43, v127
	v_cvt_pk_bf16_f32 v42, v42, v43
	ds_write_b16 v222, v42 offset:1152
	ds_write_b16_d16_hi v222, v42 offset:1216
	v_mul_f32_e32 v44, v44, v128
	v_mul_f32_e32 v45, v45, v129
	v_cvt_pk_bf16_f32 v44, v44, v45
	ds_write_b16 v222, v44 offset:1536
	ds_write_b16_d16_hi v222, v44 offset:1600
	v_mul_f32_e32 v46, v46, v130
	v_mul_f32_e32 v47, v47, v131
	v_cvt_pk_bf16_f32 v46, v46, v47
	ds_write_b16 v222, v46 offset:1664
	ds_write_b16_d16_hi v222, v46 offset:1728
	s_waitcnt lgkmcnt(0)
	ds_read_b128 v[132:135], v223
	ds_read_b128 v[136:139], v223 offset:1024
	s_waitcnt lgkmcnt(1)
	global_store_dwordx4 v224, v[132:135], s[0:1] offset:128
	s_waitcnt lgkmcnt(0)
	global_store_dwordx4 v229, v[136:139], s[0:1] offset:128
	v_mul_f32_e32 v48, v48, v116
	v_mul_f32_e32 v49, v49, v117
	v_cvt_pk_bf16_f32 v48, v48, v49
	ds_write_b16 v222, v48 offset:0
	ds_write_b16_d16_hi v222, v48 offset:64
	v_mul_f32_e32 v50, v50, v118
	v_mul_f32_e32 v51, v51, v119
	v_cvt_pk_bf16_f32 v50, v50, v51
	ds_write_b16 v222, v50 offset:128
	ds_write_b16_d16_hi v222, v50 offset:192
	v_mul_f32_e32 v52, v52, v120
	v_mul_f32_e32 v53, v53, v121
	v_cvt_pk_bf16_f32 v52, v52, v53
	ds_write_b16 v222, v52 offset:512
	ds_write_b16_d16_hi v222, v52 offset:576
	v_mul_f32_e32 v54, v54, v122
	v_mul_f32_e32 v55, v55, v123
	v_cvt_pk_bf16_f32 v54, v54, v55
	ds_write_b16 v222, v54 offset:640
	ds_write_b16_d16_hi v222, v54 offset:704
	v_mul_f32_e32 v56, v56, v124
	v_mul_f32_e32 v57, v57, v125
	v_cvt_pk_bf16_f32 v56, v56, v57
	ds_write_b16 v222, v56 offset:1024
	ds_write_b16_d16_hi v222, v56 offset:1088
	v_mul_f32_e32 v58, v58, v126
	v_mul_f32_e32 v59, v59, v127
	v_cvt_pk_bf16_f32 v58, v58, v59
	ds_write_b16 v222, v58 offset:1152
	ds_write_b16_d16_hi v222, v58 offset:1216
	v_mul_f32_e32 v60, v60, v128
	v_mul_f32_e32 v61, v61, v129
	v_cvt_pk_bf16_f32 v60, v60, v61
	ds_write_b16 v222, v60 offset:1536
	ds_write_b16_d16_hi v222, v60 offset:1600
	v_mul_f32_e32 v62, v62, v130
	v_mul_f32_e32 v63, v63, v131
	v_cvt_pk_bf16_f32 v62, v62, v63
	ds_write_b16 v222, v62 offset:1664
	ds_write_b16_d16_hi v222, v62 offset:1728
	s_waitcnt lgkmcnt(0)
	ds_read_b128 v[132:135], v223
	ds_read_b128 v[136:139], v223 offset:1024
	s_waitcnt lgkmcnt(1)
	global_store_dwordx4 v224, v[132:135], s[0:1] offset:192
	s_waitcnt lgkmcnt(0)
	global_store_dwordx4 v229, v[136:139], s[0:1] offset:192
	s_cmp_lt_u32 s26, 4
	s_cbranch_scc1 .Lat2_unit_1
	s_branch .Lat2_done_7
